# tile K-loops issue loads up front; attention K/V staging loads hoisted (prompt and sample); phase-2 sample-state items before the segment item on odd workgroups
# speedup vs baseline: 1.0265x; 1.0124x over previous
.LBB0_76:
	v_lshl_add_u64 v[66:67], v[38:39], 0, v[36:37]
	v_lshl_add_u64 v[70:71], v[38:39], 0, v[34:35]
	global_load_dwordx4 v[72:75], v[66:67], off offset:-128
	global_load_dwordx4 v[76:79], v[70:71], off
	global_load_dwordx4 v[80:83], v[66:67], off offset:-96
	global_load_dwordx4 v[84:87], v[70:71], off offset:32
	global_load_dwordx4 v[88:91], v[66:67], off offset:-64
	global_load_dwordx4 v[92:95], v[70:71], off offset:64
	global_load_dwordx4 v[96:99], v[66:67], off offset:-32
	global_load_dwordx4 v[100:103], v[70:71], off offset:96
	global_load_dwordx4 v[104:107], v[66:67], off
	global_load_dwordx4 v[108:111], v[70:71], off offset:128
	global_load_dwordx4 v[112:115], v[66:67], off offset:32
	global_load_dwordx4 v[116:119], v[70:71], off offset:160
	global_load_dwordx4 v[120:123], v[66:67], off offset:64
	global_load_dwordx4 v[124:127], v[66:67], off offset:96
	global_load_dwordx4 v[128:131], v[70:71], off offset:192
	global_load_dwordx4 v[132:135], v[70:71], off offset:224
	s_addk_i32 s2, 0x80
	s_mov_b64 s[4:5], 0x100
	s_cmpk_lt_u32 s2, 0xe0
	v_lshl_add_u64 v[38:39], v[38:39], 0, s[4:5]
	s_waitcnt vmcnt(14)
	v_mfma_f32_32x32x16_bf16 v[0:15], v[72:75], v[76:79], v[0:15]
	s_waitcnt vmcnt(12)
	v_mfma_f32_32x32x16_bf16 v[16:31], v[80:83], v[84:87], v[16:31]
	s_waitcnt vmcnt(10)
	v_mfma_f32_32x32x16_bf16 v[0:15], v[88:91], v[92:95], v[0:15]
	s_waitcnt vmcnt(8)
	v_mfma_f32_32x32x16_bf16 v[16:31], v[96:99], v[100:103], v[16:31]
	s_waitcnt vmcnt(6)
	v_mfma_f32_32x32x16_bf16 v[0:15], v[104:107], v[108:111], v[0:15]
	s_waitcnt vmcnt(4)
	v_mfma_f32_32x32x16_bf16 v[16:31], v[112:115], v[116:119], v[16:31]
	s_waitcnt vmcnt(1)
	v_mfma_f32_32x32x16_bf16 v[0:15], v[120:123], v[128:131], v[0:15]
	s_waitcnt vmcnt(0)
	v_mfma_f32_32x32x16_bf16 v[16:31], v[124:127], v[132:135], v[16:31]
	s_cbranch_scc1 .LBB0_76
	s_nop 10
	v_add_f32_e32 v0, v0, v16
	v_add_f32_e32 v1, v1, v17
	v_add_f32_e32 v2, v2, v18
	v_add_f32_e32 v3, v3, v19
	v_add_f32_e32 v4, v4, v20
	v_add_f32_e32 v5, v5, v21
	v_add_f32_e32 v6, v6, v22
	v_add_f32_e32 v7, v7, v23
	v_add_f32_e32 v10, v10, v26
	v_add_f32_e32 v11, v11, v27
	v_add_f32_e32 v12, v12, v28
	v_add_f32_e32 v13, v13, v29
	v_add_f32_e32 v14, v14, v30
	v_add_f32_e32 v15, v15, v31
	v_add_f32_e32 v8, v8, v24
	v_add_f32_e32 v9, v9, v25
	s_barrier
	ds_write2st64_b32 v41, v0, v1 offset1:1
	ds_write2st64_b32 v41, v2, v3 offset0:2 offset1:3
	ds_write2st64_b32 v41, v4, v5 offset0:4 offset1:5
	ds_write2st64_b32 v41, v6, v7 offset0:6 offset1:7
	ds_write2st64_b32 v41, v8, v9 offset0:8 offset1:9
	ds_write2st64_b32 v41, v10, v11 offset0:10 offset1:11
	ds_write2st64_b32 v41, v12, v13 offset0:12 offset1:13
	ds_write2st64_b32 v41, v14, v15 offset0:14 offset1:15
	s_waitcnt lgkmcnt(0)
	s_barrier
	ds_read2st64_b32 v[10:11], v42 offset1:1
	ds_read2st64_b32 v[14:15], v42 offset0:16 offset1:17
	ds_read2st64_b32 v[4:5], v42 offset0:18 offset1:19
	ds_read2st64_b32 v[6:7], v42 offset0:2 offset1:3
	ds_read2st64_b32 v[16:17], v42 offset0:32 offset1:33
	ds_read2st64_b32 v[12:13], v42 offset0:48 offset1:49
	ds_read2st64_b32 v[0:1], v42 offset0:50 offset1:51
	ds_read2st64_b32 v[2:3], v42 offset0:34 offset1:35
	s_lshl_b32 s2, s42, 3
	s_andn2_b32 s2, s2, 31
	v_or_b32_e32 v144, s2, v40
	s_ashr_i32 s2, s42, 8
	s_cmp_lg_u32 s2, 1
	s_cselect_b64 s[36:37], -1, 0
	v_mov_b32_e32 v20, 0
	s_and_b64 vcc, exec, s[36:37]
	s_cbranch_vccnz .LBB0_79
	v_lshl_add_u64 v[8:9], v[144:145], 2, s[8:9]
	v_add_co_u32_e32 v8, vcc, 0xffffe000, v8
	s_nop 1
	v_addc_co_u32_e32 v9, vcc, -1, v9, vcc
	global_load_dword v20, v[8:9], off

.LBB0_298:
	s_cmp_gt_i32 s6, 2
	s_cselect_b64 s[0:1], -1, 0
	s_cmp_lt_i32 s7, 2
	s_cselect_b64 s[2:3], -1, 0
	s_or_b64 s[0:1], s[0:1], s[2:3]
	s_and_b64 vcc, exec, s[0:1]
	s_cbranch_vccnz .LBB0_398
	s_mov_b32 s2, 0
	v_writelane_b32 v255, s2, 63
	v_readlane_b32 s0, v254, 10
	s_cmpk_gt_i32 s0, 0x1bf
	v_readlane_b32 s1, v254, 11
	s_cbranch_scc1 .LBB0_307
	v_readlane_b32 s2, v254, 0
	s_bitcmp1_b32 s2, 0
	s_cbranch_scc0 .Lp2_pass1
	s_mov_b32 s2, 1
	v_writelane_b32 v255, s2, 63
	s_branch .LBB0_307
.Lp2_pass1:
	v_readlane_b32 s0, v254, 10
	s_mov_b32 s2, s0
	s_mul_hi_i32 s0, s0, 0x92492493
	v_readlane_b32 s1, v254, 11
	s_add_i32 s0, s0, s2
	s_lshr_b32 s1, s0, 31
	s_ashr_i32 s0, s0, 2
	s_add_i32 s0, s0, s1
	s_add_i32 s4, s0, s2
	v_readlane_b32 s0, v254, 15
	v_readlane_b32 s1, v254, 16
	v_mov_b32_e32 v0, 0
	s_load_dwordx2 s[0:1], s[0:1], 0xa8
	v_readlane_b32 s2, v254, 7
	v_mbcnt_lo_u32_b32 v0, -1, v0
	v_mbcnt_hi_u32_b32 v2, -1, v0
	s_ashr_i32 s5, s4, 31
	v_add_u32_e32 v71, s2, v2
	s_lshr_b32 s2, s5, 29
	s_add_i32 s2, s4, s2
	s_ashr_i32 s3, s2, 3
	s_and_b32 s2, s2, 0x7ffff8
	v_and_b32_e32 v5, 0x7f, v71
	s_sub_i32 s2, s4, s2
	s_and_b32 s7, s3, 15
	s_lshl_b32 s3, s3, 8
	v_ashrrev_i32_e32 v64, 6, v71
	v_and_b32_e32 v4, 31, v2
	s_add_i32 s8, s91, 0x11800
	s_and_b32 s3, s3, 0xfffff000
	s_lshl_b32 s2, s2, 9
	v_lshlrev_b32_e32 v6, 2, v5
	v_and_b32_e32 v72, 63, v2
	s_add_i32 s10, s3, s2
	v_lshl_add_u32 v65, v71, 2, s8
	v_add_u32_e32 v73, s8, v6
	s_movk_i32 s8, 0x90
	v_mov_b32_e32 v7, s91
	v_lshrrev_b32_e32 v2, 1, v2
	v_lshl_or_b32 v8, v64, 5, v4
	v_ashrrev_i32_e32 v3, 7, v71
	s_add_i32 s6, s91, 0x11c00
	s_add_i32 s9, s91, 0x11e00
	s_mulk_i32 s7, 0x4080
	v_mad_u32_u24 v7, v5, s8, v7
	v_and_b32_e32 v2, 16, v2
	v_mul_lo_u32 v8, v8, s8
	s_ashr_i32 s8, s10, 31
	v_lshlrev_b32_e32 v0, 5, v3
	v_add_u32_e32 v74, s6, v2
	v_add_u32_e32 v77, s6, v6
	s_add_u32 s6, s10, s7
	v_ashrrev_i32_e32 v1, 31, v0
	s_addc_u32 s7, s8, 0
	v_lshl_add_u64 v[0:1], s[6:7], 0, v[0:1]
	v_lshlrev_b64 v[0:1], 8, v[0:1]
	v_mov_b32_e32 v70, 0
	s_movk_i32 s2, 0x80
	v_lshlrev_b32_e32 v3, 6, v3
	v_add_u32_e32 v8, s91, v8
	v_add_u32_e32 v9, s91, v2
	v_mul_u32_u24_e32 v4, 0x90, v4
	v_lshl_or_b32 v0, v5, 1, v0
	v_cmp_gt_u32_e64 s[2:3], s2, v71
	v_add_u32_e32 v75, s9, v2
	v_add_u32_e32 v76, s9, v6
	s_waitcnt lgkmcnt(0)
	v_lshl_add_u64 v[66:67], s[0:1], 0, v[0:1]
	s_mov_b64 s[6:7], 0
	s_mov_b32 s10, 0x96e0000
	s_mov_b32 s11, 0x96e1000
	s_mov_b32 s12, 0xd760000
	s_mov_b32 s13, 0xd761000
	s_mov_b32 s14, 0xc2a00000
	v_mov_b32_e32 v78, 0x42a00000
	v_add_u32_e32 v79, v7, v3
	v_add_u32_e32 v80, v8, v2
	v_add_u32_e32 v81, v9, v4
	v_mov_b32_e32 v0, 0
	v_mov_b32_e32 v1, v70
	v_mov_b32_e32 v2, 0
	v_mov_b32_e32 v3, v70
	v_mov_b32_e32 v4, 0
	v_mov_b32_e32 v5, v70
	v_mov_b32_e32 v6, 0
	v_mov_b32_e32 v7, v70
	v_mov_b32_e32 v8, 0
	v_mov_b32_e32 v9, v70
	v_mov_b32_e32 v10, 0
	v_mov_b32_e32 v11, v70
	v_mov_b32_e32 v12, 0
	v_mov_b32_e32 v13, v70
	v_mov_b32_e32 v14, 0
	v_mov_b32_e32 v15, v70
	v_mov_b32_e32 v48, 0
	v_mov_b32_e32 v49, v70
	v_mov_b32_e32 v50, 0
	v_mov_b32_e32 v51, v70
	v_mov_b32_e32 v52, 0
	v_mov_b32_e32 v53, v70
	v_mov_b32_e32 v54, 0
	v_mov_b32_e32 v55, v70
	v_mov_b32_e32 v56, 0
	v_mov_b32_e32 v57, v70
	v_mov_b32_e32 v58, 0
	v_mov_b32_e32 v59, v70
	v_mov_b32_e32 v60, 0
	v_mov_b32_e32 v61, v70
	v_mov_b32_e32 v62, 0
	v_mov_b32_e32 v63, v70
	v_mov_b32_e32 v32, 0
	v_mov_b32_e32 v33, v70
	v_mov_b32_e32 v34, 0
	v_mov_b32_e32 v35, v70
	v_mov_b32_e32 v36, 0
	v_mov_b32_e32 v37, v70
	v_mov_b32_e32 v38, 0
	v_mov_b32_e32 v39, v70
	v_mov_b32_e32 v40, 0
	v_mov_b32_e32 v41, v70
	v_mov_b32_e32 v42, 0
	v_mov_b32_e32 v43, v70
	v_mov_b32_e32 v44, 0
	v_mov_b32_e32 v45, v70
	v_mov_b32_e32 v46, 0
	v_mov_b32_e32 v47, v70
	v_mov_b32_e32 v16, 0
	v_mov_b32_e32 v17, v70
	v_mov_b32_e32 v18, 0
	v_mov_b32_e32 v19, v70
	v_mov_b32_e32 v20, 0
	v_mov_b32_e32 v21, v70
	v_mov_b32_e32 v22, 0
	v_mov_b32_e32 v23, v70
	v_mov_b32_e32 v24, 0
	v_mov_b32_e32 v25, v70
	v_mov_b32_e32 v26, 0
	v_mov_b32_e32 v27, v70
	v_mov_b32_e32 v28, 0
	v_mov_b32_e32 v29, v70
	v_mov_b32_e32 v30, 0
	v_mov_b32_e32 v31, v70
	s_branch .LBB0_302

.LBB0_307:
	v_readlane_b32 s2, v255, 63
	s_cmp_eq_u32 s2, 2
	s_cbranch_scc1 .Lp2_end
	v_readlane_b32 s0, v254, 12
	v_readlane_b32 s1, v254, 13
	s_cmpk_eq_i32 s0, 0x200
	s_mov_b64 s[0:1], -1
	s_cbranch_scc1 .LBB0_320
	v_readlane_b32 s0, v254, 10
	s_cmpk_gt_i32 s0, 0x7ff
	v_readlane_b32 s1, v254, 11
	s_cbranch_scc1 .LBB0_319
	v_readlane_b32 s0, v254, 15
	v_readlane_b32 s1, v254, 16
	s_load_dwordx2 s[0:1], s[0:1], 0xa8
	v_mbcnt_lo_u32_b32 v0, -1, 0
	s_movk_i32 s14, 0x80
	s_mov_b32 s19, 0x4480000
	v_mov_b32_e32 v80, 0x358637bd
	s_waitcnt lgkmcnt(0)
	s_add_u32 s15, s0, 0x5660000
	s_addc_u32 s16, s1, 0
	s_add_u32 s17, s0, 0x15860000
	s_addc_u32 s18, s1, 0
	v_readlane_b32 s0, v254, 10
	v_readlane_b32 s1, v254, 11
	s_mov_b32 s6, s0
	s_ashr_i32 s7, s0, 31
	v_readlane_b32 s0, v254, 12
	s_mov_b32 s4, s0
	s_mov_b32 s2, s4
	v_readlane_b32 s1, v254, 13
	v_writelane_b32 v254, s2, 12
	s_ashr_i32 s5, s0, 31
	s_lshl_b64 s[0:1], s[6:7], 16
	v_writelane_b32 v254, s3, 13
	s_mov_b32 s2, s6
	v_writelane_b32 v254, s2, 10
	s_lshl_b64 s[4:5], s[4:5], 16
	s_mov_b32 s20, 0x800000
	v_mbcnt_hi_u32_b32 v81, -1, v0
	v_writelane_b32 v254, s3, 11
	s_mov_b32 s21, s6
	s_branch .LBB0_311

.LBB0_344:
	v_readlane_b32 s2, v255, 63
	s_cmp_eq_u32 s2, 1
	s_cbranch_scc0 .Lp2_end
	s_mov_b32 s2, 2
	v_writelane_b32 v255, s2, 63
	s_branch .Lp2_pass1

.LBB0_505:
	global_load_dwordx4 v[72:75], v[40:41], off offset:-128
	global_load_dwordx4 v[76:79], v[38:39], off offset:-128
	global_load_dwordx4 v[80:83], v[40:41], off offset:-96
	global_load_dwordx4 v[84:87], v[38:39], off offset:-96
	global_load_dwordx4 v[88:91], v[40:41], off offset:-64
	global_load_dwordx4 v[92:95], v[38:39], off offset:-64
	global_load_dwordx4 v[96:99], v[40:41], off offset:-32
	global_load_dwordx4 v[100:103], v[38:39], off offset:-32
	global_load_dwordx4 v[104:107], v[40:41], off
	global_load_dwordx4 v[108:111], v[38:39], off
	global_load_dwordx4 v[112:115], v[40:41], off offset:32
	global_load_dwordx4 v[116:119], v[38:39], off offset:32
	global_load_dwordx4 v[120:123], v[40:41], off offset:64
	global_load_dwordx4 v[124:127], v[40:41], off offset:96
	global_load_dwordx4 v[128:131], v[38:39], off offset:64
	global_load_dwordx4 v[132:135], v[38:39], off offset:96
	s_addk_i32 s11, 0x80
	s_cmpk_lt_u32 s11, 0x1e0
	v_lshl_add_u64 v[40:41], v[40:41], 0, s[2:3]
	v_lshl_add_u64 v[38:39], v[38:39], 0, s[2:3]
	s_waitcnt vmcnt(14)
	v_mfma_f32_32x32x16_bf16 v[0:15], v[72:75], v[76:79], v[0:15]
	s_waitcnt vmcnt(12)
	v_mfma_f32_32x32x16_bf16 v[16:31], v[80:83], v[84:87], v[16:31]
	s_waitcnt vmcnt(10)
	v_mfma_f32_32x32x16_bf16 v[0:15], v[88:91], v[92:95], v[0:15]
	s_waitcnt vmcnt(8)
	v_mfma_f32_32x32x16_bf16 v[16:31], v[96:99], v[100:103], v[16:31]
	s_waitcnt vmcnt(6)
	v_mfma_f32_32x32x16_bf16 v[0:15], v[104:107], v[108:111], v[0:15]
	s_waitcnt vmcnt(4)
	v_mfma_f32_32x32x16_bf16 v[16:31], v[112:115], v[116:119], v[16:31]
	s_waitcnt vmcnt(1)
	v_mfma_f32_32x32x16_bf16 v[0:15], v[120:123], v[128:131], v[0:15]
	s_waitcnt vmcnt(0)
	v_mfma_f32_32x32x16_bf16 v[16:31], v[124:127], v[132:135], v[16:31]
	s_cbranch_scc1 .LBB0_505
	s_nop 10
	v_add_f32_e32 v0, v0, v16
	v_add_f32_e32 v1, v1, v17
	v_add_f32_e32 v2, v2, v18
	v_add_f32_e32 v3, v3, v19
	v_add_f32_e32 v4, v4, v20
	v_add_f32_e32 v5, v5, v21
	v_add_f32_e32 v6, v6, v22
	v_add_f32_e32 v7, v7, v23
	v_add_f32_e32 v8, v8, v24
	v_add_f32_e32 v9, v9, v25
	v_add_f32_e32 v10, v10, v26
	v_add_f32_e32 v11, v11, v27
	v_add_f32_e32 v12, v12, v28
	v_add_f32_e32 v13, v13, v29
	v_add_f32_e32 v14, v14, v30
	v_add_f32_e32 v15, v15, v31
	s_barrier
	ds_write2st64_b32 v43, v0, v1 offset1:1
	ds_write2st64_b32 v43, v2, v3 offset0:2 offset1:3
	ds_write2st64_b32 v43, v4, v5 offset0:4 offset1:5
	ds_write2st64_b32 v43, v6, v7 offset0:6 offset1:7
	ds_write2st64_b32 v43, v8, v9 offset0:8 offset1:9
	ds_write2st64_b32 v43, v10, v11 offset0:10 offset1:11
	ds_write2st64_b32 v43, v12, v13 offset0:12 offset1:13
	ds_write2st64_b32 v43, v14, v15 offset0:14 offset1:15
	s_waitcnt lgkmcnt(0)
	s_barrier
	ds_read2st64_b32 v[0:1], v44 offset1:1
	ds_read2st64_b32 v[2:3], v44 offset0:16 offset1:17
	ds_read2st64_b32 v[4:5], v44 offset0:32 offset1:33
	ds_read2st64_b32 v[6:7], v44 offset0:48 offset1:49
	ds_read2st64_b32 v[8:9], v44 offset0:18 offset1:19
	ds_read2st64_b32 v[10:11], v44 offset0:2 offset1:3
	s_waitcnt lgkmcnt(4)
	v_add_f32_e32 v0, v0, v2
	ds_read2st64_b32 v[12:13], v44 offset0:50 offset1:51
	ds_read2st64_b32 v[14:15], v44 offset0:34 offset1:35
	s_waitcnt lgkmcnt(5)
	v_add_f32_e32 v0, v0, v4
	s_waitcnt lgkmcnt(4)
	v_add_f32_e32 v4, v0, v6
	v_add_f32_e32 v0, v1, v3
	v_add_f32_e32 v0, v0, v5
	v_add_f32_e32 v5, v0, v7
	s_waitcnt lgkmcnt(2)
	v_add_f32_e32 v0, v10, v8
	s_lshl_b32 s12, s10, 5
	s_waitcnt lgkmcnt(0)
	v_add_f32_e32 v0, v0, v14
	s_lshl_b32 s11, s10, 3
	s_and_b32 s12, s12, 0x60
	v_add_f32_e32 v6, v0, v12
	v_add_f32_e32 v0, v11, v9
	v_add_f32_e32 v0, v0, v15
	v_add_u32_e32 v8, s12, v45
	s_and_b32 s11, s11, 0xe0
	v_add_f32_e32 v7, v0, v13
	v_add_u32_e32 v0, 0x4000, v8
	v_or_b32_e32 v1, s11, v42
	s_ashr_i32 s14, s10, 5
	v_lshlrev_b32_e32 v36, 1, v1
	v_ashrrev_i32_e32 v1, 31, v0
	v_mad_i64_i32 v[0:1], s[12:13], s14, v47, v[0:1]
	v_lshl_add_u64 v[2:3], s[0:1], 0, v[36:37]
	v_lshlrev_b64 v[0:1], 9, v[0:1]
	v_cvt_pk_bf16_f32 v4, v4, s0
	v_lshl_add_u64 v[0:1], v[2:3], 0, v[0:1]
	global_store_short v[0:1], v4, off
	v_add_u32_e32 v0, 0x4001, v8
	v_ashrrev_i32_e32 v1, 31, v0
	v_mad_i64_i32 v[0:1], s[12:13], s14, v47, v[0:1]
	v_lshlrev_b64 v[0:1], 9, v[0:1]
	v_cvt_pk_bf16_f32 v4, v5, s0
	v_lshl_add_u64 v[0:1], v[2:3], 0, v[0:1]
	global_store_short v[0:1], v4, off
	v_add_u32_e32 v0, 0x4002, v8
	v_ashrrev_i32_e32 v1, 31, v0
	v_mad_i64_i32 v[0:1], s[12:13], s14, v47, v[0:1]
	v_lshlrev_b64 v[0:1], 9, v[0:1]
	v_cvt_pk_bf16_f32 v4, v6, s0
	v_lshl_add_u64 v[0:1], v[2:3], 0, v[0:1]
	global_store_short v[0:1], v4, off
	v_add_u32_e32 v0, 0x4003, v8
	v_ashrrev_i32_e32 v1, 31, v0
	v_mad_i64_i32 v[0:1], s[12:13], s14, v47, v[0:1]
	v_readlane_b32 s12, v254, 12
	v_lshlrev_b64 v[0:1], 9, v[0:1]
	s_add_i32 s10, s10, s12
	s_add_i32 s4, s4, s5
	s_add_i32 s6, s6, s7
	v_cvt_pk_bf16_f32 v4, v7, s0
	v_lshl_add_u64 v[0:1], v[2:3], 0, v[0:1]
	s_cmpk_lt_i32 s10, 0x80
	v_readlane_b32 s13, v254, 13
	global_store_short v[0:1], v4, off
	s_cbranch_scc1 .LBB0_504
	v_readlane_b32 s10, v254, 10
	v_readlane_b32 s11, v254, 11

.LBB0_725:
	global_load_dwordx4 v[80:83], v[44:45], off offset:-128
	global_load_dwordx4 v[84:87], v[42:43], off offset:-128
	global_load_dwordx4 v[88:91], v[44:45], off offset:-96
	global_load_dwordx4 v[92:95], v[42:43], off offset:-96
	global_load_dwordx4 v[96:99], v[44:45], off offset:-64
	global_load_dwordx4 v[100:103], v[42:43], off offset:-64
	global_load_dwordx4 v[104:107], v[44:45], off offset:-32
	global_load_dwordx4 v[108:111], v[42:43], off offset:-32
	global_load_dwordx4 v[112:115], v[44:45], off
	global_load_dwordx4 v[116:119], v[42:43], off
	global_load_dwordx4 v[120:123], v[44:45], off offset:32
	global_load_dwordx4 v[124:127], v[42:43], off offset:32
	global_load_dwordx4 v[128:131], v[44:45], off offset:64
	global_load_dwordx4 v[132:135], v[44:45], off offset:96
	global_load_dwordx4 v[136:139], v[42:43], off offset:64
	global_load_dwordx4 v[140:143], v[42:43], off offset:96
	s_addk_i32 s6, 0x80
	s_cmpk_lt_u32 s6, 0xe0
	v_lshl_add_u64 v[44:45], v[44:45], 0, s[2:3]
	v_lshl_add_u64 v[42:43], v[42:43], 0, s[2:3]
	s_waitcnt vmcnt(14)
	v_mfma_f32_32x32x16_bf16 v[0:15], v[80:83], v[84:87], v[0:15]
	s_waitcnt vmcnt(12)
	v_mfma_f32_32x32x16_bf16 v[16:31], v[88:91], v[92:95], v[16:31]
	s_waitcnt vmcnt(10)
	v_mfma_f32_32x32x16_bf16 v[0:15], v[96:99], v[100:103], v[0:15]
	s_waitcnt vmcnt(8)
	v_mfma_f32_32x32x16_bf16 v[16:31], v[104:107], v[108:111], v[16:31]
	s_waitcnt vmcnt(6)
	v_mfma_f32_32x32x16_bf16 v[0:15], v[112:115], v[116:119], v[0:15]
	s_waitcnt vmcnt(4)
	v_mfma_f32_32x32x16_bf16 v[16:31], v[120:123], v[124:127], v[16:31]
	s_waitcnt vmcnt(1)
	v_mfma_f32_32x32x16_bf16 v[0:15], v[128:131], v[136:139], v[0:15]
	s_waitcnt vmcnt(0)
	v_mfma_f32_32x32x16_bf16 v[16:31], v[132:135], v[140:143], v[16:31]
	s_cbranch_scc1 .LBB0_725
	s_lshl_b32 s7, s16, 5
	s_and_b32 s7, s7, 0x60
	v_or_b32_e32 v32, s7, v71
	s_nop 7
	v_add_f32_e32 v0, v0, v16
	v_add_f32_e32 v1, v1, v17
	v_add_f32_e32 v8, v8, v24
	v_add_f32_e32 v9, v9, v25
	v_lshlrev_b32_e32 v32, 9, v32
	v_add_f32_e32 v2, v2, v18
	v_add_f32_e32 v3, v3, v19
	v_add_f32_e32 v4, v4, v20
	v_add_f32_e32 v5, v5, v21
	v_add_f32_e32 v6, v6, v22
	v_add_f32_e32 v7, v7, v23
	v_add_f32_e32 v10, v10, v26
	v_add_f32_e32 v11, v11, v27
	v_add_f32_e32 v12, v12, v28
	v_add_f32_e32 v13, v13, v29
	v_add_f32_e32 v14, v14, v30
	v_add_f32_e32 v15, v15, v31
	s_barrier
	ds_write2st64_b32 v63, v0, v1 offset1:1
	ds_write2st64_b32 v63, v2, v3 offset0:2 offset1:3
	ds_write2st64_b32 v63, v4, v5 offset0:4 offset1:5
	ds_write2st64_b32 v63, v6, v7 offset0:6 offset1:7
	ds_write2st64_b32 v63, v8, v9 offset0:8 offset1:9
	ds_write2st64_b32 v63, v10, v11 offset0:10 offset1:11
	ds_write2st64_b32 v63, v12, v13 offset0:12 offset1:13
	ds_write2st64_b32 v63, v14, v15 offset0:14 offset1:15
	v_lshl_add_u64 v[8:9], v[34:35], 0, v[32:33]
	s_waitcnt lgkmcnt(0)
	s_barrier
	global_load_dwordx4 v[0:3], v[8:9], off
	s_lshl_b32 s6, s16, 3
	s_andn2_b32 s6, s6, 31
	v_or_b32_e32 v42, s6, v62
	v_ashrrev_i32_e32 v43, 31, v42
	v_lshlrev_b64 v[4:5], 9, v[42:43]
	v_lshl_add_u64 v[24:25], v[36:37], 0, v[4:5]
	global_load_dwordx4 v[4:7], v[24:25], off
	global_load_dwordx4 v[16:19], v[8:9], off offset:32
	global_load_dwordx4 v[20:23], v[24:25], off offset:32
	global_load_dwordx4 v[72:75], v[8:9], off offset:64
	global_load_dwordx4 v[76:79], v[24:25], off offset:64
	global_load_dwordx4 v[80:83], v[8:9], off offset:96
	global_load_dwordx4 v[84:87], v[24:25], off offset:96
	v_add_u32_e32 v32, s7, v65
	v_add_u32_e32 v60, 0x4000, v32
	v_ashrrev_i32_e32 v61, 31, v60
	ds_read2st64_b32 v[52:53], v64 offset1:1
	ds_read2st64_b32 v[54:55], v64 offset0:16 offset1:17
	ds_read2st64_b32 v[44:45], v64 offset0:18 offset1:19
	ds_read2st64_b32 v[46:47], v64 offset0:2 offset1:3
	ds_read2st64_b32 v[56:57], v64 offset0:32 offset1:33
	ds_read2st64_b32 v[58:59], v64 offset0:48 offset1:49
	ds_read2st64_b32 v[48:49], v64 offset0:50 offset1:51
	ds_read2st64_b32 v[50:51], v64 offset0:34 offset1:35
	s_waitcnt lgkmcnt(0)
	s_barrier
	s_waitcnt vmcnt(4)
	v_mfma_f32_32x32x16_bf16 v[16:31], v[16:19], v[20:23], 0
	v_mfma_f32_32x32x16_bf16 v[0:15], v[0:3], v[4:7], 0
	s_waitcnt vmcnt(2)
	v_mfma_f32_32x32x16_bf16 v[0:15], v[72:75], v[76:79], v[0:15]
	v_lshlrev_b64 v[72:73], 10, v[60:61]
	v_lshl_add_u64 v[72:73], v[72:73], 0, v[42:43]
	v_lshlrev_b64 v[72:73], 1, v[72:73]
	v_lshl_add_u64 v[74:75], s[4:5], 0, v[72:73]
	s_waitcnt vmcnt(0)
	v_mfma_f32_32x32x16_bf16 v[16:31], v[80:83], v[84:87], v[16:31]
	s_nop 11
	v_add_f32_e32 v0, v0, v16
	v_add_f32_e32 v1, v1, v17
	v_add_f32_e32 v2, v2, v18
	v_add_f32_e32 v3, v3, v19
	v_add_f32_e32 v4, v4, v20
	v_add_f32_e32 v5, v5, v21
	v_add_f32_e32 v6, v6, v22
	v_add_f32_e32 v7, v7, v23
	v_add_f32_e32 v8, v8, v24
	v_add_f32_e32 v9, v9, v25
	v_add_f32_e32 v10, v10, v26
	v_add_f32_e32 v11, v11, v27
	v_add_f32_e32 v12, v12, v28
	v_add_f32_e32 v13, v13, v29
	v_add_f32_e32 v14, v14, v30
	v_add_f32_e32 v15, v15, v31
	ds_write2st64_b32 v63, v0, v1 offset1:1
	ds_write2st64_b32 v63, v2, v3 offset0:2 offset1:3
	ds_write2st64_b32 v63, v4, v5 offset0:4 offset1:5
	ds_write2st64_b32 v63, v6, v7 offset0:6 offset1:7
	ds_write2st64_b32 v63, v8, v9 offset0:8 offset1:9
	ds_write2st64_b32 v63, v10, v11 offset0:10 offset1:11
	ds_write2st64_b32 v63, v12, v13 offset0:12 offset1:13
	ds_write2st64_b32 v63, v14, v15 offset0:14 offset1:15
	s_waitcnt lgkmcnt(0)
	s_barrier
	global_load_ushort v16, v[74:75], off
	ds_read2st64_b32 v[8:9], v64 offset1:1
	ds_read2st64_b32 v[10:11], v64 offset0:16 offset1:17
	v_add_f32_e32 v0, v52, v54
	v_add_f32_e32 v0, v0, v56
	v_add_f32_e32 v4, v0, v58
	v_mul_f32_e32 v4, 0xbfb8aa3b, v4
	s_waitcnt lgkmcnt(0)
	v_add_f32_e32 v8, v8, v10
	v_exp_f32_e32 v10, v4
	ds_read2st64_b32 v[0:1], v64 offset0:18 offset1:19
	ds_read2st64_b32 v[2:3], v64 offset0:2 offset1:3
	ds_read2st64_b32 v[12:13], v64 offset0:32 offset1:33
	ds_read2st64_b32 v[14:15], v64 offset0:48 offset1:49
	ds_read2st64_b32 v[4:5], v64 offset0:50 offset1:51
	ds_read2st64_b32 v[6:7], v64 offset0:34 offset1:35
	v_add_f32_e32 v10, 1.0, v10
	v_rcp_f32_e32 v10, v10
	s_waitcnt lgkmcnt(3)
	v_add_f32_e32 v8, v8, v12
	s_waitcnt lgkmcnt(2)
	v_add_f32_e32 v8, v8, v14
	s_waitcnt vmcnt(0)
	v_lshlrev_b32_e32 v12, 16, v16
	v_fmac_f32_e32 v12, v10, v8
	v_mul_f32_e32 v8, v12, v12
	ds_bpermute_b32 v8, v66, v8
	v_lshl_add_u64 v[16:17], s[8:9], 0, v[72:73]
	s_waitcnt lgkmcnt(0)
	v_fmac_f32_e32 v8, v12, v12
	ds_bpermute_b32 v10, v67, v8
	v_cvt_pk_bf16_f32 v12, v12, s0
	global_store_short v[16:17], v12, off
	s_waitcnt lgkmcnt(0)
	v_add_f32_e32 v8, v8, v10
	ds_bpermute_b32 v10, v68, v8
	s_waitcnt lgkmcnt(0)
	v_add_f32_e32 v8, v8, v10
	ds_bpermute_b32 v10, v69, v8
	s_waitcnt lgkmcnt(0)
	v_add_f32_e32 v8, v8, v10
	ds_bpermute_b32 v10, v70, v8
	s_and_saveexec_b64 s[6:7], vcc
	s_cbranch_execz .LBB0_728
	s_waitcnt lgkmcnt(0)
	v_add_f32_e32 v8, v8, v10
	v_lshl_add_u64 v[16:17], v[60:61], 2, s[10:11]
	global_atomic_add_f32 v[16:17], v8, off

.LBB0_798:
	global_load_dwordx4 v[72:75], v[38:39], off offset:-128
	global_load_dwordx4 v[76:79], v[36:37], off offset:-128
	global_load_dwordx4 v[80:83], v[38:39], off offset:-96
	global_load_dwordx4 v[84:87], v[36:37], off offset:-96
	global_load_dwordx4 v[88:91], v[38:39], off offset:-64
	global_load_dwordx4 v[92:95], v[36:37], off offset:-64
	global_load_dwordx4 v[96:99], v[38:39], off offset:-32
	global_load_dwordx4 v[100:103], v[36:37], off offset:-32
	global_load_dwordx4 v[104:107], v[38:39], off
	global_load_dwordx4 v[108:111], v[36:37], off
	global_load_dwordx4 v[112:115], v[38:39], off offset:32
	global_load_dwordx4 v[116:119], v[36:37], off offset:32
	global_load_dwordx4 v[120:123], v[38:39], off offset:64
	global_load_dwordx4 v[124:127], v[38:39], off offset:96
	global_load_dwordx4 v[128:131], v[36:37], off offset:64
	global_load_dwordx4 v[132:135], v[36:37], off offset:96
	s_addk_i32 s6, 0x80
	s_cmpk_lt_u32 s6, 0xe0
	v_lshl_add_u64 v[38:39], v[38:39], 0, s[52:53]
	v_lshl_add_u64 v[36:37], v[36:37], 0, s[52:53]
	s_waitcnt vmcnt(14)
	v_mfma_f32_32x32x16_bf16 v[0:15], v[72:75], v[76:79], v[0:15]
	s_waitcnt vmcnt(12)
	v_mfma_f32_32x32x16_bf16 v[16:31], v[80:83], v[84:87], v[16:31]
	s_waitcnt vmcnt(10)
	v_mfma_f32_32x32x16_bf16 v[0:15], v[88:91], v[92:95], v[0:15]
	s_waitcnt vmcnt(8)
	v_mfma_f32_32x32x16_bf16 v[16:31], v[96:99], v[100:103], v[16:31]
	s_waitcnt vmcnt(6)
	v_mfma_f32_32x32x16_bf16 v[0:15], v[104:107], v[108:111], v[0:15]
	s_waitcnt vmcnt(4)
	v_mfma_f32_32x32x16_bf16 v[16:31], v[112:115], v[116:119], v[16:31]
	s_waitcnt vmcnt(1)
	v_mfma_f32_32x32x16_bf16 v[0:15], v[120:123], v[128:131], v[0:15]
	s_waitcnt vmcnt(0)
	v_mfma_f32_32x32x16_bf16 v[16:31], v[124:127], v[132:135], v[16:31]
	s_cbranch_scc1 .LBB0_798
	s_nop 10
	v_add_f32_e32 v0, v0, v16
	v_add_f32_e32 v1, v1, v17
	v_add_f32_e32 v2, v2, v18
	v_add_f32_e32 v3, v3, v19
	v_add_f32_e32 v4, v4, v20
	v_add_f32_e32 v5, v5, v21
	v_add_f32_e32 v6, v6, v22
	v_add_f32_e32 v7, v7, v23
	v_add_f32_e32 v8, v8, v24
	v_add_f32_e32 v9, v9, v25
	v_add_f32_e32 v10, v10, v26
	v_add_f32_e32 v11, v11, v27
	v_add_f32_e32 v12, v12, v28
	v_add_f32_e32 v13, v13, v29
	v_add_f32_e32 v14, v14, v30
	v_add_f32_e32 v15, v15, v31
	s_barrier
	ds_write2st64_b32 v43, v0, v1 offset1:1
	ds_write2st64_b32 v43, v2, v3 offset0:2 offset1:3
	ds_write2st64_b32 v43, v4, v5 offset0:4 offset1:5
	ds_write2st64_b32 v43, v6, v7 offset0:6 offset1:7
	ds_write2st64_b32 v43, v8, v9 offset0:8 offset1:9
	ds_write2st64_b32 v43, v10, v11 offset0:10 offset1:11
	ds_write2st64_b32 v43, v12, v13 offset0:12 offset1:13
	ds_write2st64_b32 v43, v14, v15 offset0:14 offset1:15
	s_waitcnt lgkmcnt(0)
	s_barrier
	ds_read2st64_b32 v[18:19], v44 offset1:1
	ds_read2st64_b32 v[20:21], v44 offset0:16 offset1:17
	ds_read2st64_b32 v[22:23], v44 offset0:32 offset1:33
	ds_read2st64_b32 v[24:25], v44 offset0:48 offset1:49
	s_lshl_b32 s6, s28, 5
	s_and_b32 s29, s6, 0x60
	s_waitcnt lgkmcnt(2)
	v_add_f32_e32 v0, v18, v20
	s_waitcnt lgkmcnt(1)
	v_add_f32_e32 v0, v0, v22
	s_waitcnt lgkmcnt(0)
	v_add_f32_e32 v1, v0, v24
	v_add_u32_e32 v0, s29, v45
	v_add_u32_e32 v26, 0x4000, v0
	v_ashrrev_i32_e32 v27, 31, v26
	v_lshl_add_u64 v[10:11], v[26:27], 2, s[24:25]
	ds_read2st64_b32 v[2:3], v44 offset0:2 offset1:3
	ds_read2st64_b32 v[4:5], v44 offset0:18 offset1:19
	ds_read2st64_b32 v[6:7], v44 offset0:34 offset1:35
	ds_read2st64_b32 v[8:9], v44 offset0:50 offset1:51
	global_load_dword v10, v[10:11], off
	s_lshl_b32 s15, s28, 3
	s_and_b32 s14, s15, 0xffffffe0
	s_cmpk_gt_i32 s14, 0x7ff
	s_cselect_b64 s[8:9], -1, 0
	s_cmpk_lt_i32 s14, 0x800
	s_cselect_b64 s[6:7], -1, 0
	s_and_b32 s10, s28, 0x1fffffe0
	s_cmpk_lg_i32 s10, 0x200
	s_cselect_b64 s[12:13], -1, 0
	s_cmpk_eq_i32 s10, 0x200
	s_cselect_b64 s[10:11], -1, 0
	s_or_b64 s[6:7], s[10:11], s[6:7]
	s_bitcmp0_b32 s28, 2
	s_cselect_b64 s[10:11], -1, 0
	s_and_b64 s[10:11], s[10:11], s[6:7]
	s_waitcnt vmcnt(0)
	v_fmamk_f32 v10, v10, 0x3a800000, v230
	v_cmp_gt_f32_e32 vcc, s90, v10
	v_mul_f32_e32 v11, 0x4b800000, v10
	s_nop 0
	v_cndmask_b32_e32 v10, v10, v11, vcc
	v_rsq_f32_e32 v10, v10
	s_nop 0
	v_mul_f32_e32 v11, 0x45800000, v10
	v_cndmask_b32_e32 v10, v10, v11, vcc
	v_mul_f32_e32 v18, v1, v10
	v_cndmask_b32_e64 v1, 0, 1, s[10:11]
	v_cmp_ne_u32_e64 s[6:7], 1, v1
	s_andn2_b64 vcc, exec, s[10:11]
	s_cbranch_vccnz .LBB0_805
	v_and_b32_e32 v10, 64, v231
	v_xor_b32_e32 v1, 8, v231
	v_add_u32_e32 v10, 64, v10
	v_cmp_lt_i32_e32 vcc, v1, v10
	s_nop 1
	v_cndmask_b32_e32 v1, v231, v1, vcc
	v_lshlrev_b32_e32 v1, 2, v1
	ds_bpermute_b32 v10, v1, v18
	v_mul_f32_e32 v1, v40, v18
	s_waitcnt lgkmcnt(0)
	v_mul_f32_e32 v10, v41, v10
	s_and_saveexec_b64 s[10:11], s[2:3]
	s_xor_b64 s[10:11], exec, s[10:11]
	v_add_f32_e32 v1, v1, v10
	v_cndmask_b32_e64 v18, v18, v1, s[4:5]
	s_andn2_saveexec_b64 s[10:11], s[10:11]
	v_sub_f32_e32 v18, v1, v10
	s_or_b64 exec, exec, s[10:11]

.LBB0_2000:
	s_and_b32 s16, s0, 3
	v_writelane_b32 v254, s0, 49
	s_lshl_b32 s0, s16, 9
	v_writelane_b32 v254, s0, 50
	v_writelane_b32 v254, s1, 51
	s_cmpk_gt_i32 s1, 0x1ff
	s_mov_b64 s[0:1], -1
	s_cbranch_scc0 .LBB0_2022
	v_readlane_b32 s0, v254, 15
	v_readlane_b32 s1, v254, 16
	v_mov_b32_e32 v0, v97
	s_load_dwordx2 s[0:1], s[0:1], 0xa8
	v_readlane_b32 s4, v254, 51
	v_mbcnt_lo_u32_b32 v0, -1, v0
	s_add_i32 s2, s4, 0xfffffe00
	v_mbcnt_hi_u32_b32 v12, -1, v0
	v_readlane_b32 s3, v254, 7
	s_lshr_b32 s8, s2, 2
	s_movk_i32 s2, 0x800
	v_add_u32_e32 v8, s3, v12
	s_and_b32 s14, s4, 3
	s_or_b32 s36, s8, 0x4000
	v_cmp_gt_i32_e32 vcc, s2, v8
	s_waitcnt lgkmcnt(0)
	s_barrier
	s_and_saveexec_b64 s[2:3], vcc
	s_cbranch_execz .LBB0_2008
	s_lshl_b32 s4, s36, 9
	s_add_u32 s4, s0, s4
	s_addc_u32 s5, s1, 0
	s_lshl_b32 s15, s14, 6
	s_lshl_b32 s6, s14, 7
	s_add_u32 s4, s4, s6
	s_addc_u32 s5, s5, 0
	s_add_u32 s4, s4, 0x198e0000
	s_addc_u32 s5, s5, 0
	s_lshl_b32 s7, s8, 9
	s_add_u32 s7, s0, s7
	s_addc_u32 s9, s1, 0
	s_add_u32 s6, s7, s6
	s_addc_u32 s7, s9, 0
	s_add_u32 s6, s6, 0x1a8f0000
	v_readlane_b32 s10, v254, 46
	s_addc_u32 s7, s7, 0
	s_lshl_b32 s8, s8, 7
	s_mov_b32 s9, s37
	v_lshl_add_u32 v9, v12, 2, s10
	s_mov_b64 s[10:11], 0
	v_mov_b32_e32 v13, v8
	v_lshrrev_b32_e32 v100, 4, v8
	v_and_b32_e32 v101, 15, v8
	v_lshlrev_b32_e32 v103, 3, v101
	v_lshlrev_b32_e32 v101, 4, v101
	v_readlane_b32 s18, v254, 15
	v_readlane_b32 s19, v254, 16
	s_load_dwordx4 s[20:23], s[18:19], 0x28
	v_add_u32_e32 v102, s8, v100
	s_lshl_b32 s12, s15, 2
	v_lshl_add_u32 v102, v102, 10, v101
	v_add_u32_e32 v102, s12, v102
	s_waitcnt lgkmcnt(0)
	global_load_dwordx4 v[104:107], v102, s[20:21] offset:1024
	global_load_dwordx4 v[108:111], v102, s[22:23] offset:1024
	v_add_u32_e32 v102, 0x4000, v102
	global_load_dwordx4 v[112:115], v102, s[20:21] offset:1024
	global_load_dwordx4 v[116:119], v102, s[22:23] offset:1024
	v_add_u32_e32 v102, 0x4000, v102
	global_load_dwordx4 v[120:123], v102, s[20:21] offset:1024
	global_load_dwordx4 v[124:127], v102, s[22:23] offset:1024
	v_add_u32_e32 v102, 0x4000, v102
	global_load_dwordx4 v[128:131], v102, s[20:21] offset:1024
	global_load_dwordx4 v[132:135], v102, s[22:23] offset:1024
	v_add_u32_e32 v102, 0x4000, v102
	global_load_dwordx4 v[136:139], v102, s[20:21] offset:1024
	global_load_dwordx4 v[140:143], v102, s[22:23] offset:1024
	v_add_u32_e32 v102, 0x4000, v102
	global_load_dwordx4 v[144:147], v102, s[20:21] offset:1024
	global_load_dwordx4 v[148:151], v102, s[22:23] offset:1024
	v_add_u32_e32 v102, 0x4000, v102
	global_load_dwordx4 v[152:155], v102, s[20:21] offset:1024
	global_load_dwordx4 v[156:159], v102, s[22:23] offset:1024
	v_add_u32_e32 v102, 0x4000, v102
	v_cmp_ne_u32_e32 vcc, 15, v100
	s_and_saveexec_b64 s[10:11], vcc
	global_load_dwordx4 v[160:163], v102, s[20:21] offset:1024
	global_load_dwordx4 v[164:167], v102, s[22:23] offset:1024
	s_xor_b64 exec, exec, s[10:11]
	global_load_dwordx2 v[168:169], v103, s[4:5]
	global_load_dwordx2 v[170:171], v103, s[6:7]
	s_waitcnt vmcnt(0)
	v_lshlrev_b32_e32 v160, 16, v168
	v_and_b32_e32 v161, 0xffff0000, v168
	v_lshlrev_b32_e32 v162, 16, v169
	v_and_b32_e32 v163, 0xffff0000, v169
	v_lshlrev_b32_e32 v164, 16, v170
	v_and_b32_e32 v165, 0xffff0000, v170
	v_lshlrev_b32_e32 v166, 16, v171
	v_and_b32_e32 v167, 0xffff0000, v171
	s_mov_b64 exec, s[10:11]
	s_movk_i32 s12, 0x104
	v_mul_lo_u32 v172, v100, s12
	v_lshlrev_b32_e32 v173, 8, v100
	v_add3_u32 v172, s91, v172, v101
	v_add3_u32 v173, s91, v173, v101
	s_waitcnt vmcnt(0)
	ds_write2_b32 v172, v104, v105 offset1:1
	ds_write2_b32 v172, v106, v107 offset0:2 offset1:3
	ds_write_b128 v173, v[108:111] offset:33280
	v_add_u32_e32 v172, 0x1040, v172
	ds_write2_b32 v172, v112, v113 offset1:1
	ds_write2_b32 v172, v114, v115 offset0:2 offset1:3
	ds_write_b128 v173, v[116:119] offset:37376
	v_add_u32_e32 v172, 0x1040, v172
	ds_write2_b32 v172, v120, v121 offset1:1
	ds_write2_b32 v172, v122, v123 offset0:2 offset1:3
	ds_write_b128 v173, v[124:127] offset:41472
	v_add_u32_e32 v172, 0x1040, v172
	ds_write2_b32 v172, v128, v129 offset1:1
	ds_write2_b32 v172, v130, v131 offset0:2 offset1:3
	ds_write_b128 v173, v[132:135] offset:45568
	v_add_u32_e32 v172, 0x1040, v172
	ds_write2_b32 v172, v136, v137 offset1:1
	ds_write2_b32 v172, v138, v139 offset0:2 offset1:3
	ds_write_b128 v173, v[140:143] offset:49664
	v_add_u32_e32 v172, 0x1040, v172
	ds_write2_b32 v172, v144, v145 offset1:1
	ds_write2_b32 v172, v146, v147 offset0:2 offset1:3
	ds_write_b128 v173, v[148:151] offset:53760
	v_add_u32_e32 v172, 0x1040, v172
	ds_write2_b32 v172, v152, v153 offset1:1
	ds_write2_b32 v172, v154, v155 offset0:2 offset1:3
	ds_write_b128 v173, v[156:159] offset:57856
	v_add_u32_e32 v172, 0x1040, v172
	ds_write2_b32 v172, v160, v161 offset1:1
	ds_write2_b32 v172, v162, v163 offset0:2 offset1:3
	ds_write_b128 v173, v[164:167] offset:61952

.LBB0_2022:
	s_and_b64 vcc, exec, s[0:1]
	s_cbranch_vccz .LBB0_1999
	v_readlane_b32 s0, v254, 15
	v_readlane_b32 s1, v254, 16
	v_mov_b32_e32 v1, 0
	s_load_dwordx2 s[26:27], s[0:1], 0xa8
	v_readlane_b32 s1, v254, 51
	v_mbcnt_lo_u32_b32 v1, -1, v1
	v_mbcnt_hi_u32_b32 v25, -1, v1
	v_readlane_b32 s0, v254, 7
	s_bfe_u32 s17, s1, 0x50002
	s_lshl_b32 s20, s1, 5
	v_add_u32_e32 v27, s0, v25
	s_and_b32 s18, s1, 3
	s_lshl_b32 s0, s17, 7
	s_and_b32 s1, s20, 0xfffff000
	s_or_b32 s19, s1, s0
	s_sub_i32 s14, 0x7f, s0
	s_add_i32 s21, s19, 0xffffff80
	s_lshl_b32 s0, s18, 7
	v_and_b32_e32 v28, 7, v25
	s_waitcnt lgkmcnt(0)
	s_add_u32 s0, s26, s0
	s_addc_u32 s1, s27, 0
	v_lshlrev_b32_e32 v96, 4, v28
	v_ashrrev_i32_e32 v29, 3, v27
	v_lshl_add_u64 v[2:3], s[0:1], 0, v[96:97]
	s_mov_b64 s[0:1], 0x198e0000
	v_add_u32_e32 v6, s21, v29
	v_mov_b32_e32 v0, 0
	v_lshl_add_u64 v[22:23], v[2:3], 0, s[0:1]
	v_cmp_lt_i32_e32 vcc, s14, v29
	v_ashrrev_i32_e32 v7, 31, v6
	v_mov_b32_e32 v2, 0
	v_mov_b32_e32 v3, 0
	v_mov_b32_e32 v4, 0
	v_mov_b32_e32 v5, 0
	s_waitcnt vmcnt(63) expcnt(7) lgkmcnt(15)
	s_barrier
	v_lshlrev_b64 v[208:209], 9, v[6:7]
	v_mov_b32_e32 v212, 0x4000
	v_mov_b32_e32 v213, 0
	v_mov_b32_e32 v214, 0x810000
	v_mov_b32_e32 v215, 0
	v_lshl_add_u64 v[208:209], v[22:23], 0, v[208:209]
	v_lshl_add_u64 v[210:211], v[208:209], 0, v[214:215]
	global_load_dwordx4 v[136:139], v[208:209], off
	v_lshl_add_u64 v[208:209], v[208:209], 0, v[212:213]
	global_load_dwordx4 v[140:143], v[208:209], off
	v_lshl_add_u64 v[208:209], v[208:209], 0, v[212:213]
	global_load_dwordx4 v[144:147], v[208:209], off
	v_lshl_add_u64 v[208:209], v[208:209], 0, v[212:213]
	global_load_dwordx4 v[148:151], v[208:209], off
	v_lshl_add_u64 v[208:209], v[208:209], 0, v[212:213]
	global_load_dwordx4 v[152:155], v[208:209], off
	v_lshl_add_u64 v[208:209], v[208:209], 0, v[212:213]
	global_load_dwordx4 v[156:159], v[208:209], off
	v_lshl_add_u64 v[208:209], v[208:209], 0, v[212:213]
	global_load_dwordx4 v[160:163], v[208:209], off
	v_lshl_add_u64 v[208:209], v[208:209], 0, v[212:213]
	global_load_dwordx4 v[164:167], v[208:209], off
	global_load_dwordx4 v[168:171], v[210:211], off
	v_lshl_add_u64 v[210:211], v[210:211], 0, v[212:213]
	global_load_dwordx4 v[172:175], v[210:211], off
	v_lshl_add_u64 v[210:211], v[210:211], 0, v[212:213]
	global_load_dwordx4 v[176:179], v[210:211], off
	v_lshl_add_u64 v[210:211], v[210:211], 0, v[212:213]
	global_load_dwordx4 v[180:183], v[210:211], off
	v_lshl_add_u64 v[210:211], v[210:211], 0, v[212:213]
	global_load_dwordx4 v[184:187], v[210:211], off
	v_lshl_add_u64 v[210:211], v[210:211], 0, v[212:213]
	global_load_dwordx4 v[188:191], v[210:211], off
	v_lshl_add_u64 v[210:211], v[210:211], 0, v[212:213]
	global_load_dwordx4 v[192:195], v[210:211], off
	v_lshl_add_u64 v[210:211], v[210:211], 0, v[212:213]
	global_load_dwordx4 v[204:207], v[210:211], off
	s_and_saveexec_b64 s[0:1], vcc
	s_cbranch_execz .LBB0_2025
	v_lshlrev_b64 v[2:3], 9, v[6:7]
	v_lshl_add_u64 v[2:3], v[22:23], 0, v[2:3]
	s_waitcnt vmcnt(15)
	v_mov_b32_e32 v2, v136
	v_mov_b32_e32 v3, v137
	v_mov_b32_e32 v4, v138
	v_mov_b32_e32 v5, v139
.LBB0_2025:
	s_or_b64 exec, exec, s[0:1]
	v_lshl_add_u32 v24, v28, 4, s91
	v_add_u32_e32 v1, 0x100, v27
	v_mad_u64_u32 v[8:9], s[0:1], v29, s25, v[24:25]
	v_ashrrev_i32_e32 v30, 3, v1
	s_nop 0
	ds_write_b128 v8, v[2:5]
	v_add_u32_e32 v8, s21, v30
	v_cmp_lt_i32_e64 s[2:3], s14, v30
	v_ashrrev_i32_e32 v9, 31, v8
	v_mov_b32_e32 v1, 0
	v_mov_b32_e32 v2, 0
	v_mov_b32_e32 v3, 0
	s_and_saveexec_b64 s[0:1], s[2:3]
	s_cbranch_execz .LBB0_2027
	v_lshlrev_b64 v[0:1], 9, v[8:9]
	v_lshl_add_u64 v[0:1], v[22:23], 0, v[0:1]
	s_waitcnt vmcnt(14)
	v_mov_b32_e32 v0, v140
	v_mov_b32_e32 v1, v141
	v_mov_b32_e32 v2, v142
	v_mov_b32_e32 v3, v143
.LBB0_2027:
	s_or_b64 exec, exec, s[0:1]
	v_mad_u64_u32 v[4:5], s[0:1], v30, s25, v[24:25]
	s_nop 0
	ds_write_b128 v4, v[0:3]
	v_add_u32_e32 v0, 0x200, v27
	v_ashrrev_i32_e32 v31, 3, v0
	v_add_u32_e32 v10, s21, v31
	v_cmp_lt_i32_e64 s[4:5], s14, v31
	v_mov_b32_e32 v0, 0
	v_ashrrev_i32_e32 v11, 31, v10
	v_mov_b32_e32 v2, 0
	v_mov_b32_e32 v3, 0
	v_mov_b32_e32 v4, 0
	v_mov_b32_e32 v5, 0
	s_and_saveexec_b64 s[0:1], s[4:5]
	s_cbranch_execz .LBB0_2029
	v_lshlrev_b64 v[2:3], 9, v[10:11]
	v_lshl_add_u64 v[2:3], v[22:23], 0, v[2:3]
	s_waitcnt vmcnt(13)
	v_mov_b32_e32 v2, v144
	v_mov_b32_e32 v3, v145
	v_mov_b32_e32 v4, v146
	v_mov_b32_e32 v5, v147
.LBB0_2029:
	s_or_b64 exec, exec, s[0:1]
	v_add_u32_e32 v1, 0x300, v27
	v_mad_u64_u32 v[12:13], s[0:1], v31, s25, v[24:25]
	v_ashrrev_i32_e32 v32, 3, v1
	s_nop 0
	ds_write_b128 v12, v[2:5]
	v_add_u32_e32 v12, s21, v32
	v_cmp_lt_i32_e64 s[6:7], s14, v32
	v_ashrrev_i32_e32 v13, 31, v12
	v_mov_b32_e32 v1, 0
	v_mov_b32_e32 v2, 0
	v_mov_b32_e32 v3, 0
	s_and_saveexec_b64 s[0:1], s[6:7]
	s_cbranch_execz .LBB0_2031
	v_lshlrev_b64 v[0:1], 9, v[12:13]
	v_lshl_add_u64 v[0:1], v[22:23], 0, v[0:1]
	s_waitcnt vmcnt(12)
	v_mov_b32_e32 v0, v148
	v_mov_b32_e32 v1, v149
	v_mov_b32_e32 v2, v150
	v_mov_b32_e32 v3, v151
.LBB0_2031:
	s_or_b64 exec, exec, s[0:1]
	v_mad_u64_u32 v[4:5], s[0:1], v32, s25, v[24:25]
	s_nop 0
	ds_write_b128 v4, v[0:3]
	v_add_u32_e32 v0, 0x400, v27
	v_ashrrev_i32_e32 v33, 3, v0
	v_add_u32_e32 v14, s21, v33
	v_cmp_lt_i32_e64 s[8:9], s14, v33
	v_mov_b32_e32 v0, 0
	v_ashrrev_i32_e32 v15, 31, v14
	v_mov_b32_e32 v2, 0
	v_mov_b32_e32 v3, 0
	v_mov_b32_e32 v4, 0
	v_mov_b32_e32 v5, 0
	s_and_saveexec_b64 s[0:1], s[8:9]
	s_cbranch_execz .LBB0_2033
	v_lshlrev_b64 v[2:3], 9, v[14:15]
	v_lshl_add_u64 v[2:3], v[22:23], 0, v[2:3]
	s_waitcnt vmcnt(11)
	v_mov_b32_e32 v2, v152
	v_mov_b32_e32 v3, v153
	v_mov_b32_e32 v4, v154
	v_mov_b32_e32 v5, v155
.LBB0_2033:
	s_or_b64 exec, exec, s[0:1]
	v_add_u32_e32 v1, 0x500, v27
	v_mad_u64_u32 v[16:17], s[0:1], v33, s25, v[24:25]
	v_ashrrev_i32_e32 v34, 3, v1
	s_nop 0
	ds_write_b128 v16, v[2:5]
	v_add_u32_e32 v16, s21, v34
	v_cmp_lt_i32_e64 s[10:11], s14, v34
	v_ashrrev_i32_e32 v17, 31, v16
	v_mov_b32_e32 v1, 0
	v_mov_b32_e32 v2, 0
	v_mov_b32_e32 v3, 0
	s_and_saveexec_b64 s[0:1], s[10:11]
	s_cbranch_execz .LBB0_2035
	v_lshlrev_b64 v[0:1], 9, v[16:17]
	v_lshl_add_u64 v[0:1], v[22:23], 0, v[0:1]
	s_waitcnt vmcnt(10)
	v_mov_b32_e32 v0, v156
	v_mov_b32_e32 v1, v157
	v_mov_b32_e32 v2, v158
	v_mov_b32_e32 v3, v159
.LBB0_2035:
	s_or_b64 exec, exec, s[0:1]
	v_mad_u64_u32 v[4:5], s[0:1], v34, s25, v[24:25]
	s_nop 0
	ds_write_b128 v4, v[0:3]
	v_add_u32_e32 v0, 0x600, v27
	v_ashrrev_i32_e32 v35, 3, v0
	v_add_u32_e32 v18, s21, v35
	v_cmp_lt_i32_e64 s[12:13], s14, v35
	v_mov_b32_e32 v0, 0
	v_ashrrev_i32_e32 v19, 31, v18
	v_mov_b32_e32 v2, 0
	v_mov_b32_e32 v3, 0
	v_mov_b32_e32 v4, 0
	v_mov_b32_e32 v5, 0
	s_and_saveexec_b64 s[0:1], s[12:13]
	s_cbranch_execz .LBB0_2037
	v_lshlrev_b64 v[2:3], 9, v[18:19]
	v_lshl_add_u64 v[2:3], v[22:23], 0, v[2:3]
	s_waitcnt vmcnt(9)
	v_mov_b32_e32 v2, v160
	v_mov_b32_e32 v3, v161
	v_mov_b32_e32 v4, v162
	v_mov_b32_e32 v5, v163
.LBB0_2037:
	s_or_b64 exec, exec, s[0:1]
	v_add_u32_e32 v1, 0x700, v27
	v_mad_u64_u32 v[20:21], s[0:1], v35, s25, v[24:25]
	v_ashrrev_i32_e32 v26, 3, v1
	s_nop 0
	ds_write_b128 v20, v[2:5]
	v_add_u32_e32 v20, s21, v26
	v_cmp_lt_i32_e64 s[14:15], s14, v26
	v_ashrrev_i32_e32 v21, 31, v20
	v_mov_b32_e32 v1, 0
	v_mov_b32_e32 v2, 0
	v_mov_b32_e32 v3, 0
	s_and_saveexec_b64 s[0:1], s[14:15]
	s_cbranch_execz .LBB0_2039
	v_lshlrev_b64 v[0:1], 9, v[20:21]
	v_lshl_add_u64 v[0:1], v[22:23], 0, v[0:1]
	s_waitcnt vmcnt(8)
	v_mov_b32_e32 v0, v164
	v_mov_b32_e32 v1, v165
	v_mov_b32_e32 v2, v166
	v_mov_b32_e32 v3, v167
.LBB0_2039:
	s_or_b64 exec, exec, s[0:1]
	s_lshl_b32 s21, s18, 6
	v_mad_u64_u32 v[4:5], s[0:1], v26, s25, v[24:25]
	s_lshl_b32 s0, s21, 1
	v_lshlrev_b32_e32 v22, 3, v28
	s_add_u32 s0, s26, s0
	s_addc_u32 s1, s27, 0
	v_lshlrev_b32_e32 v96, 1, v22
	s_nop 0
	ds_write_b128 v4, v[0:3]
	v_lshl_add_u64 v[0:1], s[0:1], 0, v[96:97]
	s_mov_b64 s[0:1], 0x1a0f0000
	v_lshl_add_u64 v[22:23], v[0:1], 0, s[0:1]
	v_mov_b32_e32 v0, 0
	v_mov_b32_e32 v2, 0
	v_mov_b32_e32 v3, 0
	v_mov_b32_e32 v4, 0
	v_mov_b32_e32 v5, 0
	s_and_saveexec_b64 s[0:1], vcc
	s_cbranch_execz .LBB0_2041
	v_lshlrev_b64 v[2:3], 9, v[6:7]
	v_lshl_add_u64 v[2:3], v[22:23], 0, v[2:3]
	s_waitcnt vmcnt(7)
	v_mov_b32_e32 v2, v168
	v_mov_b32_e32 v3, v169
	v_mov_b32_e32 v4, v170
	v_mov_b32_e32 v5, v171
.LBB0_2041:
	s_or_b64 exec, exec, s[0:1]
	v_mov_b32_e32 v1, s91
	s_movk_i32 s0, 0x10c0
	v_mad_u32_u24 v6, v28, s0, v1
	v_lshl_add_u32 v1, v29, 1, v6
	s_nop 0
	ds_write_b16 v1, v2 offset:36864
	ds_write_b16_d16_hi v1, v2 offset:37400
	ds_write_b16 v1, v3 offset:37936
	ds_write_b16_d16_hi v1, v3 offset:38472
	ds_write_b16 v1, v4 offset:39008
	ds_write_b16_d16_hi v1, v4 offset:39544
	ds_write_b16 v1, v5 offset:40080
	ds_write_b16_d16_hi v1, v5 offset:40616
	v_mov_b32_e32 v1, 0
	v_mov_b32_e32 v2, 0
	v_mov_b32_e32 v3, 0
	s_and_saveexec_b64 s[0:1], s[2:3]
	s_cbranch_execz .LBB0_2043
	v_lshlrev_b64 v[0:1], 9, v[8:9]
	v_lshl_add_u64 v[0:1], v[22:23], 0, v[0:1]
	s_waitcnt vmcnt(6)
	v_mov_b32_e32 v0, v172
	v_mov_b32_e32 v1, v173
	v_mov_b32_e32 v2, v174
	v_mov_b32_e32 v3, v175
.LBB0_2043:
	s_or_b64 exec, exec, s[0:1]
	v_lshl_add_u32 v4, v30, 1, v6
	s_nop 0
	ds_write_b16 v4, v0 offset:36864
	ds_write_b16_d16_hi v4, v0 offset:37400
	ds_write_b16 v4, v1 offset:37936
	ds_write_b16_d16_hi v4, v1 offset:38472
	ds_write_b16 v4, v2 offset:39008
	ds_write_b16_d16_hi v4, v2 offset:39544
	ds_write_b16 v4, v3 offset:40080
	ds_write_b16_d16_hi v4, v3 offset:40616
	v_mov_b32_e32 v0, 0
	v_mov_b32_e32 v2, 0
	v_mov_b32_e32 v3, 0
	v_mov_b32_e32 v4, 0
	v_mov_b32_e32 v5, 0
	s_and_saveexec_b64 s[0:1], s[4:5]
	s_cbranch_execz .LBB0_2045
	v_lshlrev_b64 v[2:3], 9, v[10:11]
	v_lshl_add_u64 v[2:3], v[22:23], 0, v[2:3]
	s_waitcnt vmcnt(5)
	v_mov_b32_e32 v2, v176
	v_mov_b32_e32 v3, v177
	v_mov_b32_e32 v4, v178
	v_mov_b32_e32 v5, v179
.LBB0_2045:
	s_or_b64 exec, exec, s[0:1]
	v_lshl_add_u32 v1, v31, 1, v6
	s_nop 0
	ds_write_b16 v1, v2 offset:36864
	ds_write_b16_d16_hi v1, v2 offset:37400
	ds_write_b16 v1, v3 offset:37936
	ds_write_b16_d16_hi v1, v3 offset:38472
	ds_write_b16 v1, v4 offset:39008
	ds_write_b16_d16_hi v1, v4 offset:39544
	ds_write_b16 v1, v5 offset:40080
	ds_write_b16_d16_hi v1, v5 offset:40616
	v_mov_b32_e32 v1, 0
	v_mov_b32_e32 v2, 0
	v_mov_b32_e32 v3, 0
	s_and_saveexec_b64 s[0:1], s[6:7]
	s_cbranch_execz .LBB0_2047
	v_lshlrev_b64 v[0:1], 9, v[12:13]
	v_lshl_add_u64 v[0:1], v[22:23], 0, v[0:1]
	s_waitcnt vmcnt(4)
	v_mov_b32_e32 v0, v180
	v_mov_b32_e32 v1, v181
	v_mov_b32_e32 v2, v182
	v_mov_b32_e32 v3, v183
.LBB0_2047:
	s_or_b64 exec, exec, s[0:1]
	v_lshl_add_u32 v4, v32, 1, v6
	s_nop 0
	ds_write_b16 v4, v0 offset:36864
	ds_write_b16_d16_hi v4, v0 offset:37400
	ds_write_b16 v4, v1 offset:37936
	ds_write_b16_d16_hi v4, v1 offset:38472
	ds_write_b16 v4, v2 offset:39008
	ds_write_b16_d16_hi v4, v2 offset:39544
	ds_write_b16 v4, v3 offset:40080
	ds_write_b16_d16_hi v4, v3 offset:40616
	v_mov_b32_e32 v0, 0
	v_mov_b32_e32 v2, 0
	v_mov_b32_e32 v3, 0
	v_mov_b32_e32 v4, 0
	v_mov_b32_e32 v5, 0
	s_and_saveexec_b64 s[0:1], s[8:9]
	s_cbranch_execz .LBB0_2049
	v_lshlrev_b64 v[2:3], 9, v[14:15]
	v_lshl_add_u64 v[2:3], v[22:23], 0, v[2:3]
	s_waitcnt vmcnt(3)
	v_mov_b32_e32 v2, v184
	v_mov_b32_e32 v3, v185
	v_mov_b32_e32 v4, v186
	v_mov_b32_e32 v5, v187
.LBB0_2049:
	s_or_b64 exec, exec, s[0:1]
	v_lshl_add_u32 v1, v33, 1, v6
	s_nop 0
	ds_write_b16 v1, v2 offset:36864
	ds_write_b16_d16_hi v1, v2 offset:37400
	ds_write_b16 v1, v3 offset:37936
	ds_write_b16_d16_hi v1, v3 offset:38472
	ds_write_b16 v1, v4 offset:39008
	ds_write_b16_d16_hi v1, v4 offset:39544
	ds_write_b16 v1, v5 offset:40080
	ds_write_b16_d16_hi v1, v5 offset:40616
	v_mov_b32_e32 v1, 0
	v_mov_b32_e32 v2, 0
	v_mov_b32_e32 v3, 0
	s_and_saveexec_b64 s[0:1], s[10:11]
	s_cbranch_execz .LBB0_2051
	v_lshlrev_b64 v[0:1], 9, v[16:17]
	v_lshl_add_u64 v[0:1], v[22:23], 0, v[0:1]
	s_waitcnt vmcnt(2)
	v_mov_b32_e32 v0, v188
	v_mov_b32_e32 v1, v189
	v_mov_b32_e32 v2, v190
	v_mov_b32_e32 v3, v191
.LBB0_2051:
	s_or_b64 exec, exec, s[0:1]
	v_lshl_add_u32 v4, v34, 1, v6
	s_nop 0
	ds_write_b16 v4, v0 offset:36864
	ds_write_b16_d16_hi v4, v0 offset:37400
	ds_write_b16 v4, v1 offset:37936
	ds_write_b16_d16_hi v4, v1 offset:38472
	ds_write_b16 v4, v2 offset:39008
	ds_write_b16_d16_hi v4, v2 offset:39544
	ds_write_b16 v4, v3 offset:40080
	ds_write_b16_d16_hi v4, v3 offset:40616
	v_mov_b32_e32 v0, 0
	v_mov_b32_e32 v2, 0
	v_mov_b32_e32 v3, 0
	v_mov_b32_e32 v4, 0
	v_mov_b32_e32 v5, 0
	s_and_saveexec_b64 s[0:1], s[12:13]
	s_cbranch_execz .LBB0_2053
	v_lshlrev_b64 v[2:3], 9, v[18:19]
	v_lshl_add_u64 v[2:3], v[22:23], 0, v[2:3]
	s_waitcnt vmcnt(1)
	v_mov_b32_e32 v2, v192
	v_mov_b32_e32 v3, v193
	v_mov_b32_e32 v4, v194
	v_mov_b32_e32 v5, v195
.LBB0_2053:
	s_or_b64 exec, exec, s[0:1]
	v_lshl_add_u32 v1, v35, 1, v6
	s_nop 0
	ds_write_b16 v1, v2 offset:36864
	ds_write_b16_d16_hi v1, v2 offset:37400
	ds_write_b16 v1, v3 offset:37936
	ds_write_b16_d16_hi v1, v3 offset:38472
	ds_write_b16 v1, v4 offset:39008
	ds_write_b16_d16_hi v1, v4 offset:39544
	ds_write_b16 v1, v5 offset:40080
	ds_write_b16_d16_hi v1, v5 offset:40616
	s_mov_b32 s33, 0
	v_mov_b32_e32 v1, 0
	v_mov_b32_e32 v2, 0
	v_mov_b32_e32 v3, 0
	s_and_saveexec_b64 s[0:1], s[14:15]
	s_cbranch_execz .LBB0_2055
	v_lshlrev_b64 v[0:1], 9, v[20:21]
	v_lshl_add_u64 v[0:1], v[22:23], 0, v[0:1]
	s_waitcnt vmcnt(0)
	v_mov_b32_e32 v0, v204
	v_mov_b32_e32 v1, v205
	v_mov_b32_e32 v2, v206
	v_mov_b32_e32 v3, v207

.LBB0_2136:
	global_load_dwordx4 v[72:75], v[40:41], off offset:-128
	global_load_dwordx4 v[76:79], v[38:39], off offset:-128
	global_load_dwordx4 v[80:83], v[40:41], off offset:-96
	global_load_dwordx4 v[84:87], v[38:39], off offset:-96
	global_load_dwordx4 v[88:91], v[40:41], off offset:-64
	global_load_dwordx4 v[92:95], v[38:39], off offset:-64
	global_load_dwordx4 v[96:99], v[40:41], off offset:-32
	global_load_dwordx4 v[100:103], v[38:39], off offset:-32
	global_load_dwordx4 v[104:107], v[40:41], off
	global_load_dwordx4 v[108:111], v[38:39], off
	global_load_dwordx4 v[112:115], v[40:41], off offset:32
	global_load_dwordx4 v[116:119], v[38:39], off offset:32
	global_load_dwordx4 v[120:123], v[40:41], off offset:64
	global_load_dwordx4 v[124:127], v[40:41], off offset:96
	global_load_dwordx4 v[128:131], v[38:39], off offset:64
	global_load_dwordx4 v[132:135], v[38:39], off offset:96
	s_addk_i32 s11, 0x80
	s_cmpk_lt_u32 s11, 0x1e0
	v_lshl_add_u64 v[40:41], v[40:41], 0, s[2:3]
	v_lshl_add_u64 v[38:39], v[38:39], 0, s[2:3]
	s_waitcnt vmcnt(14)
	v_mfma_f32_32x32x16_bf16 v[0:15], v[72:75], v[76:79], v[0:15]
	s_waitcnt vmcnt(12)
	v_mfma_f32_32x32x16_bf16 v[16:31], v[80:83], v[84:87], v[16:31]
	s_waitcnt vmcnt(10)
	v_mfma_f32_32x32x16_bf16 v[0:15], v[88:91], v[92:95], v[0:15]
	s_waitcnt vmcnt(8)
	v_mfma_f32_32x32x16_bf16 v[16:31], v[96:99], v[100:103], v[16:31]
	s_waitcnt vmcnt(6)
	v_mfma_f32_32x32x16_bf16 v[0:15], v[104:107], v[108:111], v[0:15]
	s_waitcnt vmcnt(4)
	v_mfma_f32_32x32x16_bf16 v[16:31], v[112:115], v[116:119], v[16:31]
	s_waitcnt vmcnt(1)
	v_mfma_f32_32x32x16_bf16 v[0:15], v[120:123], v[128:131], v[0:15]
	s_waitcnt vmcnt(0)
	v_mfma_f32_32x32x16_bf16 v[16:31], v[124:127], v[132:135], v[16:31]
	s_cbranch_scc1 .LBB0_2136
	s_nop 10
	v_add_f32_e32 v0, v0, v16
	v_add_f32_e32 v1, v1, v17
	v_add_f32_e32 v2, v2, v18
	v_add_f32_e32 v3, v3, v19
	v_add_f32_e32 v4, v4, v20
	v_add_f32_e32 v5, v5, v21
	v_add_f32_e32 v6, v6, v22
	v_add_f32_e32 v7, v7, v23
	v_add_f32_e32 v8, v8, v24
	v_add_f32_e32 v9, v9, v25
	v_add_f32_e32 v10, v10, v26
	v_add_f32_e32 v11, v11, v27
	v_add_f32_e32 v12, v12, v28
	v_add_f32_e32 v13, v13, v29
	v_add_f32_e32 v14, v14, v30
	v_add_f32_e32 v15, v15, v31
	s_barrier
	ds_write2st64_b32 v43, v0, v1 offset1:1
	ds_write2st64_b32 v43, v2, v3 offset0:2 offset1:3
	ds_write2st64_b32 v43, v4, v5 offset0:4 offset1:5
	ds_write2st64_b32 v43, v6, v7 offset0:6 offset1:7
	ds_write2st64_b32 v43, v8, v9 offset0:8 offset1:9
	ds_write2st64_b32 v43, v10, v11 offset0:10 offset1:11
	ds_write2st64_b32 v43, v12, v13 offset0:12 offset1:13
	ds_write2st64_b32 v43, v14, v15 offset0:14 offset1:15
	s_waitcnt lgkmcnt(0)
	s_barrier
	ds_read2st64_b32 v[0:1], v44 offset1:1
	ds_read2st64_b32 v[2:3], v44 offset0:16 offset1:17
	ds_read2st64_b32 v[4:5], v44 offset0:32 offset1:33
	ds_read2st64_b32 v[6:7], v44 offset0:48 offset1:49
	ds_read2st64_b32 v[8:9], v44 offset0:18 offset1:19
	ds_read2st64_b32 v[10:11], v44 offset0:2 offset1:3
	s_waitcnt lgkmcnt(4)
	v_add_f32_e32 v0, v0, v2
	ds_read2st64_b32 v[12:13], v44 offset0:50 offset1:51
	ds_read2st64_b32 v[14:15], v44 offset0:34 offset1:35
	s_waitcnt lgkmcnt(5)
	v_add_f32_e32 v0, v0, v4
	s_waitcnt lgkmcnt(4)
	v_add_f32_e32 v4, v0, v6
	v_add_f32_e32 v0, v1, v3
	v_add_f32_e32 v0, v0, v5
	v_add_f32_e32 v5, v0, v7
	s_waitcnt lgkmcnt(2)
	v_add_f32_e32 v0, v10, v8
	s_lshl_b32 s12, s10, 5
	s_waitcnt lgkmcnt(0)
	v_add_f32_e32 v0, v0, v14
	s_lshl_b32 s11, s10, 3
	s_and_b32 s12, s12, 0x60
	v_add_f32_e32 v6, v0, v12
	v_add_f32_e32 v0, v11, v9
	v_add_f32_e32 v0, v0, v15
	v_add_u32_e32 v8, s12, v45
	s_and_b32 s11, s11, 0xe0
	v_add_f32_e32 v7, v0, v13
	v_add_u32_e32 v0, 0x4000, v8
	v_or_b32_e32 v1, s11, v42
	s_ashr_i32 s14, s10, 5
	v_lshlrev_b32_e32 v36, 1, v1
	v_ashrrev_i32_e32 v1, 31, v0
	v_mad_i64_i32 v[0:1], s[12:13], s14, v47, v[0:1]
	v_lshl_add_u64 v[2:3], s[4:5], 0, v[36:37]
	v_lshlrev_b64 v[0:1], 9, v[0:1]
	v_cvt_pk_bf16_f32 v4, v4, s0
	v_lshl_add_u64 v[0:1], v[2:3], 0, v[0:1]
	global_store_short v[0:1], v4, off
	v_add_u32_e32 v0, 0x4001, v8
	v_ashrrev_i32_e32 v1, 31, v0
	v_mad_i64_i32 v[0:1], s[12:13], s14, v47, v[0:1]
	v_lshlrev_b64 v[0:1], 9, v[0:1]
	v_cvt_pk_bf16_f32 v4, v5, s0
	v_lshl_add_u64 v[0:1], v[2:3], 0, v[0:1]
	global_store_short v[0:1], v4, off
	v_add_u32_e32 v0, 0x4002, v8
	v_ashrrev_i32_e32 v1, 31, v0
	v_mad_i64_i32 v[0:1], s[12:13], s14, v47, v[0:1]
	v_lshlrev_b64 v[0:1], 9, v[0:1]
	v_cvt_pk_bf16_f32 v4, v6, s0
	v_lshl_add_u64 v[0:1], v[2:3], 0, v[0:1]
	global_store_short v[0:1], v4, off
	v_add_u32_e32 v0, 0x4003, v8
	v_ashrrev_i32_e32 v1, 31, v0
	v_mad_i64_i32 v[0:1], s[12:13], s14, v47, v[0:1]
	v_readlane_b32 s12, v254, 12
	v_lshlrev_b64 v[0:1], 9, v[0:1]
	s_add_i32 s10, s10, s12
	s_add_i32 s6, s6, s7
	s_add_i32 s8, s8, s9
	v_cvt_pk_bf16_f32 v4, v7, s0
	v_lshl_add_u64 v[0:1], v[2:3], 0, v[0:1]
	s_cmpk_lt_i32 s10, 0x80
	v_readlane_b32 s13, v254, 13
	global_store_short v[0:1], v4, off
	s_cbranch_scc1 .LBB0_2135
	s_branch .LBB0_2138

.LBB0_2298:
	global_load_dwordx4 v[76:79], v[44:45], off offset:-128
	global_load_dwordx4 v[80:83], v[42:43], off offset:-128
	global_load_dwordx4 v[84:87], v[44:45], off offset:-96
	global_load_dwordx4 v[88:91], v[42:43], off offset:-96
	global_load_dwordx4 v[92:95], v[44:45], off offset:-64
	global_load_dwordx4 v[96:99], v[42:43], off offset:-64
	global_load_dwordx4 v[100:103], v[44:45], off offset:-32
	global_load_dwordx4 v[104:107], v[42:43], off offset:-32
	global_load_dwordx4 v[108:111], v[44:45], off
	global_load_dwordx4 v[112:115], v[42:43], off
	global_load_dwordx4 v[116:119], v[44:45], off offset:32
	global_load_dwordx4 v[120:123], v[42:43], off offset:32
	global_load_dwordx4 v[124:127], v[44:45], off offset:64
	global_load_dwordx4 v[128:131], v[44:45], off offset:96
	global_load_dwordx4 v[132:135], v[42:43], off offset:64
	global_load_dwordx4 v[136:139], v[42:43], off offset:96
	s_addk_i32 s14, 0x80
	s_cmpk_lt_u32 s14, 0xe0
	v_lshl_add_u64 v[44:45], v[44:45], 0, s[2:3]
	v_lshl_add_u64 v[42:43], v[42:43], 0, s[2:3]
	s_waitcnt vmcnt(14)
	v_mfma_f32_32x32x16_bf16 v[0:15], v[76:79], v[80:83], v[0:15]
	s_waitcnt vmcnt(12)
	v_mfma_f32_32x32x16_bf16 v[16:31], v[84:87], v[88:91], v[16:31]
	s_waitcnt vmcnt(10)
	v_mfma_f32_32x32x16_bf16 v[0:15], v[92:95], v[96:99], v[0:15]
	s_waitcnt vmcnt(8)
	v_mfma_f32_32x32x16_bf16 v[16:31], v[100:103], v[104:107], v[16:31]
	s_waitcnt vmcnt(6)
	v_mfma_f32_32x32x16_bf16 v[0:15], v[108:111], v[112:115], v[0:15]
	s_waitcnt vmcnt(4)
	v_mfma_f32_32x32x16_bf16 v[16:31], v[116:119], v[120:123], v[16:31]
	s_waitcnt vmcnt(1)
	v_mfma_f32_32x32x16_bf16 v[0:15], v[124:127], v[132:135], v[0:15]
	s_waitcnt vmcnt(0)
	v_mfma_f32_32x32x16_bf16 v[16:31], v[128:131], v[136:139], v[16:31]
	s_cbranch_scc1 .LBB0_2298
	v_readlane_b32 s16, v254, 10
	s_lshl_b32 s15, s16, 5
	s_and_b32 s15, s15, 0x60
	v_or_b32_e32 v32, s15, v50
	s_nop 6
	v_add_f32_e32 v0, v0, v16
	v_add_f32_e32 v1, v1, v17
	v_add_f32_e32 v8, v8, v24
	v_add_f32_e32 v9, v9, v25
	v_lshlrev_b32_e32 v32, 9, v32
	v_add_f32_e32 v2, v2, v18
	v_add_f32_e32 v3, v3, v19
	v_add_f32_e32 v4, v4, v20
	v_add_f32_e32 v5, v5, v21
	v_add_f32_e32 v6, v6, v22
	v_add_f32_e32 v7, v7, v23
	v_add_f32_e32 v10, v10, v26
	v_add_f32_e32 v11, v11, v27
	v_add_f32_e32 v12, v12, v28
	v_add_f32_e32 v13, v13, v29
	v_add_f32_e32 v14, v14, v30
	v_add_f32_e32 v15, v15, v31
	s_barrier
	ds_write2st64_b32 v47, v0, v1 offset1:1
	ds_write2st64_b32 v47, v2, v3 offset0:2 offset1:3
	ds_write2st64_b32 v47, v4, v5 offset0:4 offset1:5
	ds_write2st64_b32 v47, v6, v7 offset0:6 offset1:7
	ds_write2st64_b32 v47, v8, v9 offset0:8 offset1:9
	ds_write2st64_b32 v47, v10, v11 offset0:10 offset1:11
	ds_write2st64_b32 v47, v12, v13 offset0:12 offset1:13
	ds_write2st64_b32 v47, v14, v15 offset0:14 offset1:15
	v_lshl_add_u64 v[8:9], v[34:35], 0, v[32:33]
	s_waitcnt lgkmcnt(0)
	s_barrier
	global_load_dwordx4 v[0:3], v[8:9], off
	s_lshl_b32 s14, s16, 3
	s_andn2_b32 s14, s14, 31
	v_or_b32_e32 v42, s14, v46
	v_ashrrev_i32_e32 v43, 31, v42
	v_lshlrev_b64 v[4:5], 9, v[42:43]
	v_lshl_add_u64 v[10:11], v[36:37], 0, v[4:5]
	global_load_dwordx4 v[4:7], v[10:11], off
	global_load_dwordx4 v[16:19], v[8:9], off offset:32
	global_load_dwordx4 v[20:23], v[10:11], off offset:32
	global_load_dwordx4 v[52:55], v[8:9], off offset:64
	global_load_dwordx4 v[56:59], v[10:11], off offset:64
	global_load_dwordx4 v[60:63], v[8:9], off offset:96
	global_load_dwordx4 v[64:67], v[10:11], off offset:96
	v_add_u32_e32 v82, s15, v49
	v_ashrrev_i32_e32 v83, 31, v82
	v_lshlrev_b64 v[84:85], 11, v[82:83]
	v_lshl_add_u64 v[84:85], s[6:7], 0, v[84:85]
	v_lshl_add_u64 v[84:85], v[42:43], 1, v[84:85]
	ds_read2st64_b32 v[44:45], v48 offset1:1
	ds_read2st64_b32 v[68:69], v48 offset0:16 offset1:17
	ds_read2st64_b32 v[70:71], v48 offset0:18 offset1:19
	ds_read2st64_b32 v[72:73], v48 offset0:2 offset1:3
	ds_read2st64_b32 v[74:75], v48 offset0:32 offset1:33
	ds_read2st64_b32 v[76:77], v48 offset0:48 offset1:49
	ds_read2st64_b32 v[78:79], v48 offset0:50 offset1:51
	ds_read2st64_b32 v[80:81], v48 offset0:34 offset1:35
	s_waitcnt lgkmcnt(0)
	s_barrier
	v_readlane_b32 s14, v254, 12
	s_add_i32 s16, s16, s14
	v_readlane_b32 s15, v254, 13
	s_mov_b32 s14, s16
	v_readlane_b32 s17, v254, 11
	s_add_i32 s8, s8, s9
	s_add_i32 s10, s10, s11
	v_writelane_b32 v254, s14, 10
	s_cmpk_lt_i32 s16, 0x80
	s_waitcnt vmcnt(4)
	v_mfma_f32_32x32x16_bf16 v[16:31], v[16:19], v[20:23], 0
	v_writelane_b32 v254, s15, 11
	v_mfma_f32_32x32x16_bf16 v[0:15], v[0:3], v[4:7], 0
	s_waitcnt vmcnt(2)
	v_mfma_f32_32x32x16_bf16 v[0:15], v[52:55], v[56:59], v[0:15]
	v_add_co_u32_e32 v52, vcc, s12, v84
	s_nop 1
	v_addc_co_u32_e32 v53, vcc, 0, v85, vcc
	v_add_co_u32_e32 v54, vcc, s13, v84
	s_waitcnt vmcnt(0)
	v_mfma_f32_32x32x16_bf16 v[16:31], v[60:63], v[64:67], v[16:31]
	v_addc_co_u32_e32 v55, vcc, 0, v85, vcc
	s_nop 10
	v_add_f32_e32 v0, v0, v16
	v_add_f32_e32 v1, v1, v17
	v_add_f32_e32 v2, v2, v18
	v_add_f32_e32 v3, v3, v19
	v_add_f32_e32 v4, v4, v20
	v_add_f32_e32 v5, v5, v21
	v_add_f32_e32 v6, v6, v22
	v_add_f32_e32 v7, v7, v23
	v_add_f32_e32 v8, v8, v24
	v_add_f32_e32 v9, v9, v25
	v_add_f32_e32 v10, v10, v26
	v_add_f32_e32 v11, v11, v27
	v_add_f32_e32 v12, v12, v28
	v_add_f32_e32 v13, v13, v29
	v_add_f32_e32 v14, v14, v30
	v_add_f32_e32 v15, v15, v31
	ds_write2st64_b32 v47, v0, v1 offset1:1
	ds_write2st64_b32 v47, v2, v3 offset0:2 offset1:3
	ds_write2st64_b32 v47, v4, v5 offset0:4 offset1:5
	ds_write2st64_b32 v47, v6, v7 offset0:6 offset1:7
	ds_write2st64_b32 v47, v8, v9 offset0:8 offset1:9
	ds_write2st64_b32 v47, v10, v11 offset0:10 offset1:11
	ds_write2st64_b32 v47, v12, v13 offset0:12 offset1:13
	ds_write2st64_b32 v47, v14, v15 offset0:14 offset1:15
	s_waitcnt lgkmcnt(0)
	s_barrier
	global_load_ushort v24, v[54:55], off offset:-4096
	global_load_ushort v25, v[54:55], off
	global_load_ushort v26, v[54:55], off offset:2048
	global_load_ushort v27, v[52:53], off offset:2048
	v_or_b32_e32 v0, 1, v82
	v_or_b32_e32 v2, 2, v82
	v_or_b32_e32 v4, 3, v82
	v_ashrrev_i32_e32 v1, 31, v0
	v_ashrrev_i32_e32 v3, 31, v2
	v_ashrrev_i32_e32 v5, 31, v4
	v_lshl_add_u64 v[6:7], v[42:43], 2, s[0:1]
	v_lshlrev_b64 v[8:9], 12, v[82:83]
	v_lshlrev_b64 v[0:1], 12, v[0:1]
	v_lshlrev_b64 v[2:3], 12, v[2:3]
	v_lshlrev_b64 v[4:5], 12, v[4:5]
	v_add_f32_e32 v10, v44, v68
	v_add_f32_e32 v11, v45, v69
	v_add_f32_e32 v12, v72, v70
	v_add_f32_e32 v13, v73, v71
	v_lshl_add_u64 v[8:9], v[6:7], 0, v[8:9]
	v_lshl_add_u64 v[0:1], v[6:7], 0, v[0:1]
	v_lshl_add_u64 v[2:3], v[6:7], 0, v[2:3]
	v_lshl_add_u64 v[4:5], v[6:7], 0, v[4:5]
	v_add_f32_e32 v6, v10, v74
	v_add_f32_e32 v7, v11, v75
	v_add_f32_e32 v10, v12, v80
	v_add_f32_e32 v11, v13, v81
	v_add_f32_e32 v6, v6, v76
	v_add_f32_e32 v7, v7, v77
	v_add_f32_e32 v10, v10, v78
	v_add_f32_e32 v11, v11, v79
	v_mul_f32_e32 v6, 0xbfb8aa3b, v6
	v_mul_f32_e32 v7, 0xbfb8aa3b, v7
	v_mul_f32_e32 v10, 0xbfb8aa3b, v10
	v_mul_f32_e32 v11, 0xbfb8aa3b, v11
	v_exp_f32_e32 v6, v6
	v_exp_f32_e32 v7, v7
	v_exp_f32_e32 v10, v10
	v_exp_f32_e32 v11, v11
	v_add_f32_e32 v6, 1.0, v6
	v_add_f32_e32 v7, 1.0, v7
	v_add_f32_e32 v10, 1.0, v10
	v_add_f32_e32 v11, 1.0, v11
	v_rcp_f32_e32 v28, v6
	v_rcp_f32_e32 v29, v7
	v_rcp_f32_e32 v30, v10
	v_rcp_f32_e32 v31, v11
	ds_read2st64_b32 v[6:7], v48 offset1:1
	ds_read2st64_b32 v[10:11], v48 offset0:16 offset1:17
	ds_read2st64_b32 v[12:13], v48 offset0:18 offset1:19
	ds_read2st64_b32 v[14:15], v48 offset0:2 offset1:3
	ds_read2st64_b32 v[16:17], v48 offset0:32 offset1:33
	ds_read2st64_b32 v[18:19], v48 offset0:48 offset1:49
	ds_read2st64_b32 v[20:21], v48 offset0:50 offset1:51
	ds_read2st64_b32 v[22:23], v48 offset0:34 offset1:35
	s_waitcnt lgkmcnt(6)
	v_add_f32_e32 v6, v6, v10
	v_add_f32_e32 v7, v7, v11
	s_waitcnt lgkmcnt(4)
	v_add_f32_e32 v10, v14, v12
	v_add_f32_e32 v11, v15, v13
	s_waitcnt lgkmcnt(3)
	v_add_f32_e32 v6, v6, v16
	v_add_f32_e32 v7, v7, v17
	s_waitcnt lgkmcnt(0)
	v_add_f32_e32 v10, v10, v22
	v_add_f32_e32 v11, v11, v23
	v_add_f32_e32 v6, v6, v18
	v_add_f32_e32 v7, v7, v19
	v_add_f32_e32 v10, v10, v20
	v_add_f32_e32 v11, v11, v21
	s_waitcnt vmcnt(3)
	v_lshlrev_b32_e32 v12, 16, v24
	s_waitcnt vmcnt(2)
	v_lshlrev_b32_e32 v14, 16, v25
	s_waitcnt vmcnt(1)
	v_lshlrev_b32_e32 v15, 16, v26
	s_waitcnt vmcnt(0)
	v_lshlrev_b32_e32 v13, 16, v27
	v_fmac_f32_e32 v12, v28, v6
	v_fmac_f32_e32 v13, v29, v7
	v_fmac_f32_e32 v14, v30, v10
	v_fmac_f32_e32 v15, v31, v11
	global_store_dword v[8:9], v12, off
	global_store_dword v[0:1], v13, off
	global_store_dword v[2:3], v14, off
	global_store_dword v[4:5], v15, off
	s_cbranch_scc1 .LBB0_2297
	s_branch .LBB0_2300
